# same as previous best plus cheaper grid-wide-barrier fallback: only the first mismatch reporter raises the flag words
# baseline (speedup 1.0000x reference)
.LBB0_135:
	s_mov_b32 s2, 1
	v_writelane_b32 v250, s2, 60
	s_and_b32 s2, s78, 7
	s_lshl_b32 s2, s2, 2
	s_add_i32 s2, s2, 0x7fc00
	v_mov_b32_e32 v132, s2
	global_load_dword v133, v132, s[30:31] sc1
	v_readlane_b32 s2, v251, 2
	s_waitcnt vmcnt(0)
	v_readfirstlane_b32 s3, v133
	s_cmp_lg_u32 s3, s2
	s_cselect_b32 s5, 1, 0
	s_cmpk_lg_i32 s64, 0x200
	s_cselect_b32 s4, 1, 0
	s_or_b32 s5, s5, s4
	s_cmp_eq_u32 s5, 0
	s_cbranch_scc1 .Llb_ok
	s_mov_b64 s[4:5], exec
	v_readlane_b32 s2, v251, 3
	v_readlane_b32 s3, v251, 4
	s_and_b64 s[2:3], s[4:5], s[2:3]
	s_mov_b64 exec, s[2:3]
	s_cbranch_execz .Llb_rep_done
	v_mov_b32_e32 v132, 0x7fc40
	v_mov_b32_e32 v133, 1
	global_atomic_add v133, v132, v133, s[30:31] sc0
	s_waitcnt vmcnt(0)
	v_readfirstlane_b32 s2, v133
	s_cmp_lg_u32 s2, 0
	s_cbranch_scc1 .Llb_rep_done
	v_mov_b32_e32 v132, 0x7fd00
	v_mov_b32_e32 v133, 1
	global_atomic_add v132, v133, s[30:31]
	global_atomic_add v132, v133, s[30:31] offset:4
	global_atomic_add v132, v133, s[30:31] offset:8
	global_atomic_add v132, v133, s[30:31] offset:12
	global_atomic_add v132, v133, s[30:31] offset:16
	global_atomic_add v132, v133, s[30:31] offset:20
	global_atomic_add v132, v133, s[30:31] offset:24
	global_atomic_add v132, v133, s[30:31] offset:28
	global_atomic_add v132, v133, s[30:31] offset:32
	global_atomic_add v132, v133, s[30:31] offset:36
	global_atomic_add v132, v133, s[30:31] offset:40
	global_atomic_add v132, v133, s[30:31] offset:44
	global_atomic_add v132, v133, s[30:31] offset:48
	global_atomic_add v132, v133, s[30:31] offset:52
	global_atomic_add v132, v133, s[30:31] offset:56
	global_atomic_add v132, v133, s[30:31] offset:60
	global_atomic_add v132, v133, s[30:31] offset:64
	global_atomic_add v132, v133, s[30:31] offset:68
	global_atomic_add v132, v133, s[30:31] offset:72
	global_atomic_add v132, v133, s[30:31] offset:76
	global_atomic_add v132, v133, s[30:31] offset:80
	global_atomic_add v132, v133, s[30:31] offset:84
	global_atomic_add v132, v133, s[30:31] offset:88
	global_atomic_add v132, v133, s[30:31] offset:92
	global_atomic_add v132, v133, s[30:31] offset:96
	global_atomic_add v132, v133, s[30:31] offset:100
	global_atomic_add v132, v133, s[30:31] offset:104
	global_atomic_add v132, v133, s[30:31] offset:108
	global_atomic_add v132, v133, s[30:31] offset:112
	global_atomic_add v132, v133, s[30:31] offset:116
	global_atomic_add v132, v133, s[30:31] offset:120
	global_atomic_add v132, v133, s[30:31] offset:124
	global_atomic_add v132, v133, s[30:31] offset:128
	global_atomic_add v132, v133, s[30:31] offset:132
	global_atomic_add v132, v133, s[30:31] offset:136
	global_atomic_add v132, v133, s[30:31] offset:140
	global_atomic_add v132, v133, s[30:31] offset:144
	global_atomic_add v132, v133, s[30:31] offset:148
	global_atomic_add v132, v133, s[30:31] offset:152
	global_atomic_add v132, v133, s[30:31] offset:156
	global_atomic_add v132, v133, s[30:31] offset:160
	global_atomic_add v132, v133, s[30:31] offset:164
	global_atomic_add v132, v133, s[30:31] offset:168
	global_atomic_add v132, v133, s[30:31] offset:172
	global_atomic_add v132, v133, s[30:31] offset:176
	global_atomic_add v132, v133, s[30:31] offset:180
	global_atomic_add v132, v133, s[30:31] offset:184
	global_atomic_add v132, v133, s[30:31] offset:188
	global_atomic_add v132, v133, s[30:31] offset:192
	global_atomic_add v132, v133, s[30:31] offset:196
	global_atomic_add v132, v133, s[30:31] offset:200
	global_atomic_add v132, v133, s[30:31] offset:204
	global_atomic_add v132, v133, s[30:31] offset:208
	global_atomic_add v132, v133, s[30:31] offset:212
	global_atomic_add v132, v133, s[30:31] offset:216
	global_atomic_add v132, v133, s[30:31] offset:220
	global_atomic_add v132, v133, s[30:31] offset:224
	global_atomic_add v132, v133, s[30:31] offset:228
	global_atomic_add v132, v133, s[30:31] offset:232
	global_atomic_add v132, v133, s[30:31] offset:236
	global_atomic_add v132, v133, s[30:31] offset:240
	global_atomic_add v132, v133, s[30:31] offset:244
	global_atomic_add v132, v133, s[30:31] offset:248
	global_atomic_add v132, v133, s[30:31] offset:252
